# A/B on vG: attention-phase priority raise replaced by a one-time s_sleep 8 stagger for waves 0-3 (same code size)
# baseline (speedup 1.0000x reference)
; #define LAS __attribute__((address_space(3)))
; __global__ void __launch_bounds__(NTHREADS, 2) fwd_kernel(Args a) {
;     ...
;         else if (k == 1) {
;             const int lane = ltid & 63;
;             LAS float* redbase = (LAS float*)lds;
;             LAS float* rpl = (LAS float*)(lds + 4096 + wave * 4096 + 256);
;             const int ql = lane & 31, hi = lane >> 5, w = wave;
;             {
;                 const float* rp = rpb + ((size_t)layer * 8 + w) * (15 * 31);
;                 for (int i = lane; i < 15 * 31; i += 64) rpl[i] = rp[i] * LOG2E;
;                 asm volatile("s_waitcnt lgkmcnt(0)" ::: "memory");
;             }
;             int ucount = 0;
; #pragma unroll 1
;             for (int u0 = bid; u0 < 512; u0 += G, ++ucount) {
.LBB0_133:
	s_cmp_gt_i32 s16, 0
	s_mov_b64 s[10:11], -1
	s_cbranch_scc0 .LBB0_168
	v_readlane_b32 s60, v238, 0
	s_lshl_b32 s14, s50, 3
	v_readlane_b32 s8, v238, 20
	v_readlane_b32 s64, v238, 4
	v_readlane_b32 s65, v238, 5
	s_add_i32 s14, s14, s8
	s_cmp_ge_u32 s8, 4
	s_cbranch_scc1 .Lattn_prio_done
	s_sleep 8
